# up->fixup seam waits only for own group + halo neighbour group (cross-XCD neighbours write back L2 first); PP tiles remapped to the row-block owner group
# speedup vs baseline: 1.0134x; 1.0015x over previous
.LBB0_49:
	s_load_dwordx4 s[4:7], s[96:97], 0x110
	s_ashr_i32 s79, s78, 31
	s_lshl_b32 s67, s91, 3
	s_lshl_b32 s81, s94, 3
	s_lshl_b64 s[72:73], s[78:79], 3
	s_cmp_lt_u32 s1, 64
	s_cselect_b64 s[2:3], -1, 0
	s_waitcnt lgkmcnt(0)
	s_add_u32 s74, s4, 0x4200
	s_addc_u32 s75, s5, 0
	s_add_u32 s76, s4, 0x4400
	s_addc_u32 s77, s5, 0
	s_add_u32 s82, s4, 0x4500
	s_addc_u32 s83, s5, 0
	s_add_u32 s84, s4, 0x4600
	s_addc_u32 s85, s5, 0
	s_add_u32 s68, s4, 0x4700
	v_writelane_b32 v250, s2, 9
	s_addc_u32 s69, s5, 0
	s_mul_i32 s10, s91, 5
	v_writelane_b32 v250, s3, 10
	s_add_u32 s2, s4, 0x4800
	s_addc_u32 s3, s5, 0
	v_writelane_b32 v250, s2, 11
	s_movk_i32 s11, 0xc1
	v_mov_b32_e32 v225, 0
	v_writelane_b32 v250, s3, 12
	s_add_u32 s2, s4, 0x4900
	s_addc_u32 s3, s5, 0
	v_writelane_b32 v250, s2, 13
	v_mov_b32_e32 v234, 1
	v_mov_b32_e32 v243, 0x260
	v_writelane_b32 v250, s3, 14
	s_add_u32 s2, s4, 0x4a00
	s_addc_u32 s3, s5, 0
	v_writelane_b32 v250, s2, 15
	v_mov_b32_e32 v235, 0x3a27c5ac
	v_mov_b32_e32 v245, 0x3727c5ac
	v_writelane_b32 v250, s3, 16
	s_add_u32 s2, s4, 0x4b00
	s_addc_u32 s3, s5, 0
	v_writelane_b32 v250, s2, 17
	v_mov_b32_e32 v246, 0x100
	v_bfrev_b32_e32 v236, 0.5
	v_writelane_b32 v250, s3, 18
	s_add_u32 s2, s4, 0x4c00
	s_addc_u32 s3, s5, 0
	v_writelane_b32 v250, s2, 19
	v_mov_b64_e32 v[238:239], 0x200
	v_mov_b64_e32 v[240:241], 0x1ff
	v_writelane_b32 v250, s3, 20
	s_add_u32 s2, s4, 0x4d00
	s_addc_u32 s3, s5, 0
	v_writelane_b32 v250, s2, 21
	s_movk_i32 s95, 0x84
	s_mov_b32 s87, 0xf800000
	v_writelane_b32 v250, s3, 22
	s_add_u32 s2, s4, 0x4e00
	s_addc_u32 s3, s5, 0
	v_writelane_b32 v250, s2, 23
	s_mov_b32 s53, 0x5040100
	s_movk_i32 s90, 0x7f
	v_writelane_b32 v250, s3, 24
	s_add_u32 s2, s4, 0x4f00
	s_addc_u32 s3, s5, 0
	v_writelane_b32 v250, s2, 25
	s_mov_b64 s[56:57], 0x400000
	s_mov_b64 s[58:59], 0x3fffff
	v_writelane_b32 v250, s3, 26
	s_add_u32 s2, s4, 0x5000
	s_addc_u32 s3, s5, 0
	v_writelane_b32 v250, s2, 27
	s_mov_b64 s[60:61], 0x20000
	s_nop 0
	v_writelane_b32 v250, s3, 28
	s_add_u32 s2, s4, 0x5100
	s_addc_u32 s3, s5, 0
	v_writelane_b32 v250, s2, 29
	s_nop 1
	v_writelane_b32 v250, s3, 30
	s_add_u32 s2, s4, 0x5200
	s_addc_u32 s3, s5, 0
	v_writelane_b32 v250, s2, 31
	s_nop 1
	v_writelane_b32 v250, s3, 32
	s_add_u32 s2, s4, 0x5300
	s_addc_u32 s3, s5, 0
	v_writelane_b32 v250, s2, 33
	s_cmp_eq_u32 s0, 15
	s_nop 0
	v_writelane_b32 v250, s3, 34
	s_cselect_b64 s[2:3], -1, 0
	v_writelane_b32 v250, s2, 35
	s_cmp_eq_u32 s0, 14
	s_nop 0
	v_writelane_b32 v250, s3, 36
	s_cselect_b64 s[2:3], -1, 0
	v_writelane_b32 v250, s2, 37
	s_cmp_eq_u32 s0, 13
	s_nop 0
	v_writelane_b32 v250, s3, 38
	s_cselect_b64 s[2:3], -1, 0
	v_writelane_b32 v250, s2, 39
	s_cmp_eq_u32 s0, 12
	s_nop 0
	v_writelane_b32 v250, s3, 40
	s_cselect_b64 s[2:3], -1, 0
	v_writelane_b32 v250, s2, 41
	s_cmp_eq_u32 s0, 11
	s_nop 0
	v_writelane_b32 v250, s3, 42
	s_cselect_b64 s[2:3], -1, 0
	v_writelane_b32 v250, s2, 43
	s_cmp_eq_u32 s0, 10
	s_nop 0
	v_writelane_b32 v250, s3, 44
	s_cselect_b64 s[2:3], -1, 0
	v_writelane_b32 v250, s2, 45
	s_cmp_eq_u32 s0, 9
	s_nop 0
	v_writelane_b32 v250, s3, 46
	s_cselect_b64 s[2:3], -1, 0
	v_writelane_b32 v250, s2, 47
	s_cmp_eq_u32 s0, 8
	s_nop 0
	v_writelane_b32 v250, s3, 48
	s_cselect_b64 s[2:3], -1, 0
	v_writelane_b32 v250, s2, 49
	s_cmp_eq_u32 s0, 7
	s_nop 0
	v_writelane_b32 v250, s3, 50
	s_cselect_b64 s[2:3], -1, 0
	v_writelane_b32 v250, s2, 51
	s_cmp_eq_u32 s0, 6
	s_nop 0
	v_writelane_b32 v250, s3, 52
	s_cselect_b64 s[2:3], -1, 0
	v_writelane_b32 v250, s2, 53
	s_cmp_eq_u32 s0, 5
	s_nop 0
	v_writelane_b32 v250, s3, 54
	s_cselect_b64 s[2:3], -1, 0
	v_writelane_b32 v250, s2, 55
	s_cmp_eq_u32 s0, 4
	s_nop 0
	v_writelane_b32 v250, s3, 56
	s_cselect_b64 s[2:3], -1, 0
	v_writelane_b32 v250, s2, 57
	s_cmp_eq_u32 s0, 3
	s_nop 0
	v_writelane_b32 v250, s3, 58
	s_cselect_b64 s[2:3], -1, 0
	v_writelane_b32 v250, s2, 59
	s_cmp_eq_u32 s0, 2
	s_nop 0
	v_writelane_b32 v250, s3, 60
	s_cselect_b64 s[2:3], -1, 0
	v_writelane_b32 v250, s2, 61
	s_cmp_eq_u32 s0, 1
	s_nop 0
	v_writelane_b32 v250, s3, 62
	s_cselect_b64 s[2:3], -1, 0
	v_writelane_b32 v250, s2, 63
	s_cmp_eq_u32 s0, 0
	s_nop 0
	v_writelane_b32 v251, s3, 0
	s_cselect_b64 s[2:3], -1, 0
	s_lshl_b32 s0, s0, 8
	s_add_u32 s0, s14, s0
	v_writelane_b32 v251, s2, 1
	s_addc_u32 s1, s15, 0
	s_nop 0
	v_writelane_b32 v251, s3, 2
	s_add_u32 s2, s0, 0x1400
	s_addc_u32 s3, s1, 0
	v_writelane_b32 v251, s2, 3
	s_add_u32 s0, s0, 0x2400
	s_addc_u32 s1, s1, 0
	v_writelane_b32 v251, s3, 4
	v_writelane_b32 v251, s0, 5
	s_nop 1
	v_writelane_b32 v251, s1, 6
	s_add_u32 s0, s4, 0x7400
	s_addc_u32 s1, s5, 0
	v_writelane_b32 v251, s0, 7
	s_nop 1
	v_writelane_b32 v251, s1, 8
	s_add_u32 s0, s4, 0x7500
	s_addc_u32 s1, s5, 0
	v_writelane_b32 v251, s0, 9
	s_nop 1
	v_writelane_b32 v251, s1, 10
	s_lshl_b32 s0, s94, 11
	v_writelane_b32 v251, s0, 11
	s_lshl_b32 s0, s94, 10
	s_cmpk_lt_i32 s91, 0x6c0
	v_writelane_b32 v251, s0, 12
	s_cselect_b64 s[0:1], -1, 0
	v_writelane_b32 v251, s0, 13
	s_ashr_i32 s89, s91, 31
	s_nop 0
	v_writelane_b32 v251, s1, 14
	s_lshr_b32 s0, s89, 29
	s_add_i32 s0, s91, s0
	s_ashr_i32 s1, s0, 3
	s_and_b32 s0, s0, -8
	s_sub_i32 s2, s91, s0
	s_ashr_i32 s0, s94, 31
	s_cmpk_lt_i32 s91, 0x600
	v_writelane_b32 v251, s0, 15
	s_cselect_b64 s[4:5], -1, 0
	v_writelane_b32 v251, s4, 16
	s_cmpk_lt_i32 s91, 0x100
	s_nop 0
	v_writelane_b32 v251, s5, 17
	s_cselect_b64 s[4:5], -1, 0
	v_writelane_b32 v251, s4, 18
	s_cmpk_lt_i32 s91, 0x280
	s_nop 0
	v_writelane_b32 v251, s5, 19
	s_cselect_b64 s[4:5], -1, 0
	s_cmpk_lt_i32 s91, 0x200
	v_writelane_b32 v251, s4, 20
	s_cselect_b64 s[28:29], -1, 0
	s_cmpk_lt_i32 s91, 0x800
	v_writelane_b32 v251, s5, 21
	s_cselect_b64 s[4:5], -1, 0
	s_lshl_b32 s3, s2, 8
	v_writelane_b32 v251, s4, 22
	s_cmpk_lt_i32 s91, 0x400
	s_nop 0
	v_writelane_b32 v251, s5, 23
	s_cselect_b64 s[4:5], -1, 0
	s_lshl_b32 s6, s2, 7
	s_lshl_b32 s7, s2, 6
	s_lshl_b32 s64, s94, 6
	v_writelane_b32 v251, s4, 24
	s_cmpk_lt_i32 s91, 0xac0
	s_nop 0
	v_writelane_b32 v251, s5, 25
	s_cselect_b64 s[4:5], -1, 0
	v_writelane_b32 v251, s4, 26
	s_cmpk_lg_i32 s94, 0x100
	s_nop 0
	v_writelane_b32 v251, s5, 27
	s_cselect_b64 s[4:5], -1, 0
	v_writelane_b32 v251, s4, 28
	s_cmpk_eq_i32 s94, 0x100
	s_nop 0
	v_writelane_b32 v251, s5, 29
	s_cselect_b64 s[4:5], -1, 0
	s_cmpk_gt_i32 s91, 0xbf
	s_cselect_b64 s[8:9], -1, 0
	s_add_i32 s0, s10, 0xfffffd00
	s_cmpk_lt_i32 s91, 0xc0
	s_cselect_b64 s[12:13], -1, 0
	v_writelane_b32 v251, s12, 30
	s_addk_i32 s10, 0xfd01
	s_cmp_lt_i32 s2, 0
	v_writelane_b32 v251, s13, 31
	v_writelane_b32 v251, s10, 32
	s_mul_i32 s10, s2, 0x101
	s_cselect_b32 s3, s10, s3
	s_mul_i32 s10, s2, 0x81
	s_cselect_b32 s6, s10, s6
	s_mul_i32 s10, s2, 0x41
	s_cselect_b32 s7, s10, s7
	s_movk_i32 s10, 0xd9
	s_cselect_b32 s10, s10, 0xd8
	s_mul_i32 s10, s2, s10
	s_movk_i32 s12, 0x51
	s_movk_i32 s13, 0x159
	s_cselect_b32 s11, s11, 0xc0
	s_cselect_b32 s12, s12, 0x50
	s_cselect_b32 s13, s13, 0x158
	s_add_i32 s10, s10, s1
	s_mul_hi_i32 s14, s10, 0x4bda12f7
	s_lshr_b32 s15, s14, 31
	s_ashr_i32 s14, s14, 6
	s_add_i32 s14, s14, s15
	s_mul_i32 s15, s14, 0xd8
	s_sub_i32 s10, s10, s15
	s_bfe_u32 s15, s10, 0x3001c
	s_add_i32 s15, s10, s15
	s_mul_i32 s11, s2, s11
	s_and_b32 s16, s15, 0xfff8
	s_add_i32 s11, s11, s1
	s_sub_i32 s10, s10, s16
	s_mul_hi_i32 s16, s11, 0x2aaaaaab
	s_lshr_b32 s17, s16, 31
	s_ashr_i32 s16, s16, 5
	s_add_i32 s16, s16, s17
	s_mul_i32 s17, s16, 0xc0
	s_sub_i32 s11, s11, s17
	s_bfe_u32 s17, s11, 0x3001c
	s_add_i32 s17, s11, s17
	s_mul_i32 s12, s2, s12
	s_and_b32 s18, s17, 0xfff8
	s_add_i32 s12, s12, s1
	s_sub_i32 s11, s11, s18
	s_mul_hi_i32 s18, s12, 0x66666667
	s_lshr_b32 s19, s18, 31
	s_ashr_i32 s18, s18, 5
	s_add_i32 s18, s18, s19
	s_mul_i32 s19, s18, 0x50
	s_sub_i32 s12, s12, s19
	s_bfe_i32 s19, s12, 0x80000
	s_bfe_u32 s19, s19, 0x3000c
	s_add_i32 s19, s12, s19
	s_and_b32 s20, s19, 0xf8
	s_add_i32 s3, s3, s1
	s_sub_i32 s12, s12, s20
	s_ashr_i32 s20, s3, 31
	s_lshr_b32 s20, s20, 24
	s_add_i32 s20, s3, s20
	s_and_b32 s21, s20, 0xff00
	s_sub_i32 s3, s3, s21
	s_sext_i32_i16 s21, s3
	s_bfe_u32 s21, s21, 0x3001c
	s_add_i32 s21, s3, s21
	s_and_b32 s22, s21, 0xfff8
	s_sub_i32 s22, s3, s22
	s_add_i32 s3, s6, s1
	s_ashr_i32 s6, s3, 31
	s_lshr_b32 s6, s6, 23
	s_add_i32 s6, s3, s6
	s_and_b32 s23, s6, 0xfe00
	s_sub_i32 s3, s3, s23
	s_sext_i32_i16 s23, s3
	s_bfe_u32 s23, s23, 0x3001c
	s_add_i32 s23, s3, s23
	s_and_b32 s24, s23, 0xfff8
	s_sub_i32 s24, s3, s24
	s_add_i32 s3, s7, s1
	s_ashr_i32 s7, s3, 31
	s_lshr_b32 s7, s7, 26
	s_add_i32 s7, s3, s7
	s_and_b32 s25, s7, 0xffc0
	s_sub_i32 s3, s3, s25
	s_bfe_i32 s25, s3, 0x80000
	s_bfe_u32 s25, s25, 0x3000c
	s_mul_i32 s2, s2, s13
	s_add_i32 s25, s3, s25
	s_add_i32 s2, s2, s1
	s_and_b32 s26, s25, 0xf8
	s_mul_hi_i32 s1, s2, 0x2fa0be83
	s_sub_i32 s26, s3, s26
	s_lshr_b32 s3, s1, 31
	s_ashr_i32 s1, s1, 6
	s_add_i32 s1, s1, s3
	s_mul_i32 s3, s1, 0x158
	s_sub_i32 s2, s2, s3
	s_bfe_u32 s3, s2, 0x3001c
	s_add_i32 s13, s2, s3
	s_and_b32 s3, s13, 0xfff8
	s_sub_i32 s27, s2, s3
	s_lshl_b32 s2, s14, 3
	s_sext_i32_i16 s3, s10
	s_add_i32 s30, s2, s3
	s_lshl_b32 s2, s16, 3
	s_sext_i32_i16 s10, s17
	s_sext_i32_i16 s3, s11
	s_add_i32 s16, s2, s3
	s_ashr_i32 s2, s10, 6
	s_ashr_i32 s3, s2, 31
	s_lshl_b64 s[2:3], s[2:3], 23
	v_writelane_b32 v251, s2, 33
	s_lshl_b32 s1, s1, 3
	s_ashr_i32 s17, s16, 31
	v_writelane_b32 v251, s3, 34
	s_ashr_i32 s2, s10, 3
	v_writelane_b32 v251, s2, 35
	s_lshr_b32 s2, s10, 3
	s_bfe_i64 s[2:3], s[2:3], 0x100000
	s_lshl_b64 s[2:3], s[2:3], 17
	v_writelane_b32 v251, s2, 36
	s_sext_i32_i8 s10, s12
	s_sext_i32_i16 s14, s15
	v_writelane_b32 v251, s3, 37
	s_bfe_i32 s3, s19, 0x80000
	s_lshl_b32 s2, s18, 3
	s_sext_i32_i16 s3, s3
	s_add_i32 s18, s2, s10
	s_ashr_i32 s2, s3, 3
	v_writelane_b32 v251, s2, 38
	s_lshr_b32 s2, s3, 3
	s_bfe_i64 s[2:3], s[2:3], 0x100000
	s_lshl_b64 s[2:3], s[2:3], 20
	v_writelane_b32 v251, s2, 39
	s_sext_i32_i16 s10, s21
	s_ashr_i32 s19, s18, 31
	v_writelane_b32 v251, s3, 40
	s_ashr_i32 s2, s20, 8
	s_lshl_b32 s2, s2, 3
	s_sext_i32_i16 s3, s22
	s_add_i32 s12, s2, s3
	s_ashr_i32 s2, s6, 9
	s_lshl_b32 s2, s2, 3
	s_sext_i32_i16 s3, s23
	s_sext_i32_i16 s6, s24
	s_add_i32 s20, s2, s6
	s_ashr_i32 s2, s3, 3
	v_writelane_b32 v251, s2, 41
	s_lshr_b32 s2, s3, 3
	s_bfe_i64 s[2:3], s[2:3], 0x100000
	s_lshl_b64 s[2:3], s[2:3], 20
	v_writelane_b32 v251, s2, 42
	s_sext_i32_i8 s6, s26
	s_ashr_i32 s21, s20, 31
	v_writelane_b32 v251, s3, 43
	s_ashr_i32 s2, s7, 6
	s_bfe_i32 s3, s25, 0x80000
	s_lshl_b32 s2, s2, 3
	s_sext_i32_i16 s3, s3
	s_add_i32 s22, s2, s6
	s_ashr_i32 s2, s3, 3
	v_writelane_b32 v251, s2, 44
	s_lshr_b32 s2, s3, 3
	s_bfe_i64 s[24:25], s[2:3], 0x100000
	s_sext_i32_i16 s2, s27
	v_writelane_b32 v251, s28, 45
	s_add_i32 s26, s1, s2
	s_and_b64 s[2:3], s[4:5], s[8:9]
	v_writelane_b32 v251, s29, 46
	s_or_b64 s[4:5], s[4:5], s[28:29]
	v_writelane_b32 v251, s4, 47
	s_sext_i32_i16 s6, s13
	s_ashr_i32 s1, s10, 3
	v_writelane_b32 v251, s5, 48
	v_writelane_b32 v251, s1, 49
	s_ashr_i32 s1, s6, 3
	s_lshr_b32 s4, s10, 3
	v_writelane_b32 v251, s1, 50
	s_mov_b32 s10, s16
	v_writelane_b32 v251, s10, 51
	s_ashr_i32 s23, s22, 31
	s_ashr_i32 s5, s14, 3
	v_writelane_b32 v251, s11, 52
	s_lshl_b64 s[10:11], s[16:17], 17
	v_writelane_b32 v251, s10, 53
	s_lshr_b32 s6, s6, 3
	s_lshr_b32 s8, s14, 3
	v_writelane_b32 v251, s11, 54
	s_mov_b32 s10, s18
	v_writelane_b32 v251, s10, 55
	s_mov_b32 s15, 0xac00
	s_nop 0
	v_writelane_b32 v251, s11, 56
	s_lshl_b64 s[10:11], s[18:19], 20
	v_writelane_b32 v251, s10, 57
	s_nop 1
	v_writelane_b32 v251, s11, 58
	s_mov_b32 s10, s20
	v_writelane_b32 v251, s10, 59
	s_nop 1
	v_writelane_b32 v251, s11, 60
	s_lshl_b64 s[10:11], s[20:21], 20
	s_and_b64 s[2:3], s[2:3], exec
	v_writelane_b32 v251, s10, 61
	s_cselect_b32 s0, s0, s91
	s_and_b32 s1, s0, 7
	s_cmp_lg_u32 s94, 0x100
	s_cbranch_scc1 .Lmy_pp0a
	s_lshr_b32 s1, s91, 6
.Lmy_pp0a:
	v_writelane_b32 v251, s11, 62
	s_ashr_i32 s10, s0, 3
	s_cmp_lg_u32 s94, 0x100
	s_cbranch_scc1 .Lmy_pp0b
	s_and_b32 s10, s91, 7
	s_lshl_b32 s10, s10, 3
	s_bfe_u32 s98, s91, 0x30003
	s_or_b32 s10, s10, s98
.Lmy_pp0b:
	v_writelane_b32 v251, s1, 63
	s_lshl_b32 s1, s1, 17
	v_writelane_b32 v252, s1, 0
	s_mov_b32 s2, s10
	s_ashr_i32 s11, s10, 31
	v_writelane_b32 v252, s2, 1
	s_ashr_i32 s0, s14, 6
	s_sub_i32 s1, s5, 21
	v_writelane_b32 v252, s3, 2
	s_lshl_b64 s[2:3], s[10:11], 17
	s_cmp_lt_i32 s5, 24
	v_writelane_b32 v252, s2, 3
	s_cselect_b32 s0, s0, s1
	s_ashr_i32 s1, s0, 31
	v_writelane_b32 v252, s3, 4
	v_writelane_b32 v252, s5, 5
	s_lshl_b64 s[0:1], s[0:1], 26
	v_writelane_b32 v252, s0, 6
	s_ashr_i32 s31, s30, 31
	s_ashr_i32 s13, s12, 31
	v_writelane_b32 v252, s1, 7
	s_bfe_i64 s[0:1], s[8:9], 0x100000
	s_lshl_b64 s[0:1], s[0:1], 20
	v_writelane_b32 v252, s0, 8
	s_ashr_i32 s27, s26, 31
	s_ashr_i32 s65, s64, 31
	v_writelane_b32 v252, s1, 9
	s_bfe_i64 s[0:1], s[4:5], 0x100000
	s_lshl_b64 s[0:1], s[0:1], 20
	v_writelane_b32 v252, s0, 10
	s_lshl_b32 s86, s94, 7
	s_lshl_b32 s63, s94, 1
	v_writelane_b32 v252, s1, 11
	s_bfe_i64 s[0:1], s[6:7], 0x100000
	s_lshl_b64 s[0:1], s[0:1], 20
	v_writelane_b32 v252, s0, 12
	s_lshl_b32 s66, s94, 4
	s_lshl_b64 s[20:21], s[78:79], 4
	v_writelane_b32 v252, s1, 13
	s_lshl_b64 s[0:1], s[78:79], 6
	s_or_b32 s2, s0, 16
	v_writelane_b32 v252, s0, 14
	s_mov_b32 s3, s1
	s_lshl_b32 s88, s91, 7
	v_writelane_b32 v252, s1, 15
	v_writelane_b32 v252, s2, 16
	s_mul_hi_i32 s1, s78, 24
	s_mul_i32 s0, s78, 24
	v_writelane_b32 v252, s3, 17
	v_writelane_b32 v252, s0, 18
	s_lshl_b64 s[2:3], s[30:31], 20
	s_mov_b32 s11, 0
	v_writelane_b32 v252, s1, 19
	s_mul_hi_i32 s1, s78, 48
	s_mul_i32 s0, s78, 48
	v_writelane_b32 v252, s0, 20
	s_movk_i32 s4, 0x180
	s_movk_i32 s5, 0x2800
	v_writelane_b32 v252, s1, 21
	s_mul_i32 s0, s78, 0x60
	s_or_b32 s0, s0, 16
	s_mul_hi_i32 s1, s78, 0x60
	v_writelane_b32 v252, s0, 22
	s_mov_b32 s14, 0xc000
	s_mov_b32 s6, 0x3fd744fd
	v_writelane_b32 v252, s1, 23
	s_mul_i32 s0, s94, 0x14800
	s_mul_hi_i32 s1, s81, 0x2900
	v_writelane_b32 v252, s0, 24
	s_mov_b32 s10, s11
	s_nop 0
	v_writelane_b32 v252, s1, 25
	s_lshl_b32 s0, s94, 14
	v_writelane_b32 v252, s0, 26
	s_lshl_b32 s0, s91, 1
	v_writelane_b32 v252, s0, 27
	s_lshl_b32 s0, s91, 5
	v_writelane_b32 v252, s0, 28
	s_lshl_b32 s0, s91, 4
	v_writelane_b32 v252, s0, 29
	s_add_i32 s0, 0, 0x25020
	v_writelane_b32 v252, s0, 30
	s_add_i32 s0, 0, 0x25024
	v_writelane_b32 v252, s0, 31
	s_add_i32 s0, 0, 0x21000
	v_writelane_b32 v252, s0, 32
	s_add_i32 s0, 0, 0x21400
	v_writelane_b32 v252, s0, 33
	s_add_i32 s0, 0, 0x21800
	v_writelane_b32 v252, s0, 34
	s_add_i32 s0, 0, 0x21c00
	v_writelane_b32 v252, s0, 35
	s_add_i32 s0, 0, 0x22000
	v_writelane_b32 v252, s0, 36
	s_add_i32 s0, 0, 0x22400
	v_writelane_b32 v252, s0, 37
	s_add_i32 s0, 0, 0x22800
	v_writelane_b32 v252, s0, 38
	s_add_i32 s0, 0, 0x22c00
	v_writelane_b32 v252, s0, 39
	s_add_i32 s0, 0, 0x23000
	v_writelane_b32 v252, s0, 40
	s_add_i32 s0, 0, 0x23400
	v_writelane_b32 v252, s0, 41
	s_add_i32 s0, 0, 0x10800
	v_writelane_b32 v252, s0, 42
	s_add_i32 s0, 0, 0x18800
	v_writelane_b32 v252, s0, 43
	s_add_i32 s0, 0, 0x1c800
	v_writelane_b32 v252, s0, 44
	s_add_i32 s0, 0, 0x20800
	s_movk_i32 s1, 0x80
	v_writelane_b32 v252, s0, 45
	s_mov_b32 s0, s30
	v_writelane_b32 v252, s0, 46
	s_nop 1
	v_writelane_b32 v252, s1, 47
	v_writelane_b32 v252, s2, 48
	s_mov_b32 s0, s12
	s_nop 0
	v_writelane_b32 v252, s3, 49
	v_writelane_b32 v252, s0, 50
	s_lshl_b64 s[2:3], s[12:13], 20
	s_nop 0
	v_writelane_b32 v252, s1, 51
	v_writelane_b32 v252, s2, 52
	s_mov_b32 s0, s26
	s_nop 0
	v_writelane_b32 v252, s3, 53
	v_writelane_b32 v252, s0, 54
	s_lshl_b64 s[2:3], s[26:27], 20
	s_nop 0
	v_writelane_b32 v252, s1, 55
	v_writelane_b32 v252, s2, 56
	s_mov_b32 s0, s64
	s_nop 0
	v_writelane_b32 v252, s3, 57
	v_writelane_b32 v252, s22, 58
	s_lshl_b64 s[2:3], s[22:23], 20
	s_nop 0
	v_writelane_b32 v252, s23, 59
	v_writelane_b32 v252, s2, 60
	s_nop 1
	v_writelane_b32 v252, s3, 61
	v_writelane_b32 v252, s24, 62
	s_lshl_b64 s[2:3], s[24:25], 20
	v_writelane_b32 v253, s2, 0
	v_writelane_b32 v252, s25, 63
	s_mov_b64 s[24:25], 0x80
	v_writelane_b32 v253, s3, 1
	s_lshl_b64 s[2:3], s[78:79], 5
	v_writelane_b32 v253, s2, 2
	s_nop 1
	v_writelane_b32 v253, s3, 3
	s_lshl_b64 s[2:3], s[78:79], 7
	v_writelane_b32 v253, s2, 4
	s_nop 1
	v_writelane_b32 v253, s3, 5
	s_lshl_b64 s[2:3], s[64:65], 12
	v_writelane_b32 v253, s2, 6
	s_nop 1
	v_writelane_b32 v253, s3, 7
	s_mov_b64 s[2:3], 0
	v_writelane_b32 v253, s2, 8
	s_nop 1
	v_writelane_b32 v253, s3, 9
	v_writelane_b32 v253, s67, 10
	v_writelane_b32 v253, s74, 11
	s_nop 1
	v_writelane_b32 v253, s75, 12
	v_writelane_b32 v253, s76, 13
	s_nop 1
	v_writelane_b32 v253, s77, 14
	v_writelane_b32 v253, s82, 15
	s_nop 1
	v_writelane_b32 v253, s83, 16
	v_writelane_b32 v253, s84, 17
	s_nop 1
	v_writelane_b32 v253, s85, 18
	v_writelane_b32 v253, s68, 19
	s_nop 1
	v_writelane_b32 v253, s69, 20
	v_writelane_b32 v253, s0, 21
	s_nop 1
	v_writelane_b32 v253, s1, 22
	v_writelane_b32 v253, s86, 23
	v_writelane_b32 v253, s63, 24
	v_writelane_b32 v253, s66, 25
	v_writelane_b32 v253, s78, 26
	s_nop 1
	v_writelane_b32 v253, s79, 27
	v_writelane_b32 v253, s72, 28
	s_nop 1
	v_writelane_b32 v253, s73, 29
	v_writelane_b32 v253, s88, 30
	v_writelane_b32 v253, s20, 31
	s_nop 1
	v_writelane_b32 v253, s21, 32
	s_branch .LBB0_54

.LBB0_851:
	v_readlane_b32 s0, v253, 37
	v_readlane_b32 s16, v250, 0
	s_or_b32 s0, s0, 4
	v_readlane_b32 s19, v250, 3
	s_cmp_ge_i32 s0, s19
	v_readlane_b32 s17, v250, 1
	v_readlane_b32 s18, v250, 2
	s_cbranch_scc1 .LBB0_907
	s_waitcnt vmcnt(0)
	v_readlane_b32 s2, v253, 40
	v_readlane_b32 s3, v253, 41
	s_and_b64 vcc, exec, s[2:3]
	s_waitcnt vmcnt(0) lgkmcnt(0)
	s_barrier
	s_cbranch_vccnz .LBB0_906
	s_cmp_lg_u32 s101, 0
	s_cbranch_scc1 .Lmy_gchk_4
	s_mov_b32 s101, 2
	s_cmp_lg_u32 s94, 0x100
	s_cbranch_scc1 .Lmy_gchk_4
	v_readlane_b32 s8, v250, 0
	v_readlane_b32 s9, v250, 1
	s_mov_b32 s2, -1
	v_mbcnt_lo_u32_b32 v0, s2, 0
	v_mbcnt_hi_u32_b32 v0, s2, v0
	v_lshlrev_b32_e32 v0, 2, v0
	s_add_u32 s8, s8, 0x60000
	s_addc_u32 s9, s9, 0
	global_load_dword v1, v0, s[8:9] sc0 sc1
	global_load_dword v2, v0, s[8:9] offset:256 sc0 sc1
	global_load_dword v3, v0, s[8:9] offset:512 sc0 sc1
	global_load_dword v4, v0, s[8:9] offset:768 sc0 sc1
	v_and_b32_e32 v5, 28, v0
	global_load_dword v5, v5, s[8:9] sc0 sc1
	s_waitcnt vmcnt(0)
	v_cmp_eq_u32_e64 s[12:13], v1, v5
	s_nop 1
	v_cmp_ne_u32_e32 vcc, 0, v1
	v_cmp_eq_u32_e64 s[2:3], v1, v2
	s_and_b64 s[2:3], s[2:3], s[12:13]
	v_cmp_eq_u32_e64 s[12:13], v1, v3
	s_and_b64 s[2:3], s[2:3], vcc
	v_cmp_eq_u32_e64 s[8:9], v1, v4
	s_and_b64 s[2:3], s[2:3], s[12:13]
	s_and_b64 s[2:3], s[2:3], s[8:9]
	s_cmp_eq_u64 s[2:3], -1
	s_cbranch_scc0 .Lmy_gchk_4
	s_mov_b32 s101, 1

.LBB0_1900:
	v_readlane_b32 s0, v253, 37
	v_readlane_b32 s16, v250, 0
	s_or_b32 s0, s0, 10
	v_readlane_b32 s19, v250, 3
	s_cmp_ge_i32 s0, s19
	v_readlane_b32 s17, v250, 1
	v_readlane_b32 s18, v250, 2
	s_cbranch_scc1 .LBB0_1956
	s_waitcnt vmcnt(0)
	v_readlane_b32 s2, v253, 40
	v_readlane_b32 s3, v253, 41
	s_and_b64 vcc, exec, s[2:3]
	s_waitcnt vmcnt(0) lgkmcnt(0)
	s_barrier
	s_cbranch_vccnz .LBB0_1955
	s_cmp_lg_u32 s101, 0
	s_cbranch_scc1 .Lmy_gchk_0
	s_mov_b32 s101, 2
	s_cmp_lg_u32 s94, 0x100
	s_cbranch_scc1 .Lmy_gchk_0
	v_readlane_b32 s8, v250, 0
	v_readlane_b32 s9, v250, 1
	s_mov_b32 s2, -1
	v_mbcnt_lo_u32_b32 v0, s2, 0
	v_mbcnt_hi_u32_b32 v0, s2, v0
	v_lshlrev_b32_e32 v0, 2, v0
	s_add_u32 s8, s8, 0x60000
	s_addc_u32 s9, s9, 0
	global_load_dword v1, v0, s[8:9] sc0 sc1
	global_load_dword v2, v0, s[8:9] offset:256 sc0 sc1
	global_load_dword v3, v0, s[8:9] offset:512 sc0 sc1
	global_load_dword v4, v0, s[8:9] offset:768 sc0 sc1
	v_and_b32_e32 v5, 28, v0
	global_load_dword v5, v5, s[8:9] sc0 sc1
	s_waitcnt vmcnt(0)
	v_cmp_eq_u32_e64 s[12:13], v1, v5
	s_nop 1
	v_cmp_ne_u32_e32 vcc, 0, v1
	v_cmp_eq_u32_e64 s[2:3], v1, v2
	s_and_b64 s[2:3], s[2:3], s[12:13]
	v_cmp_eq_u32_e64 s[12:13], v1, v3
	s_and_b64 s[2:3], s[2:3], vcc
	v_cmp_eq_u32_e64 s[8:9], v1, v4
	s_and_b64 s[2:3], s[2:3], s[12:13]
	s_and_b64 s[2:3], s[2:3], s[8:9]
	s_cmp_eq_u64 s[2:3], -1
	s_cbranch_scc0 .Lmy_gchk_0
	s_mov_b32 s101, 1

.LBB0_1978:
	v_readlane_b32 s0, v253, 37
	v_readlane_b32 s16, v250, 0
	s_or_b32 s0, s0, 11
	v_readlane_b32 s19, v250, 3
	s_cmp_ge_i32 s0, s19
	v_readlane_b32 s17, v250, 1
	v_readlane_b32 s18, v250, 2
	s_cbranch_scc1 .LBB0_2034
	s_waitcnt vmcnt(0)
	v_readlane_b32 s2, v253, 40
	v_readlane_b32 s3, v253, 41
	s_and_b64 vcc, exec, s[2:3]
	s_waitcnt vmcnt(0) lgkmcnt(0)
	s_barrier
	s_cbranch_vccnz .LBB0_2033
	s_cmp_lg_u32 s101, 0
	s_cbranch_scc1 .Lmy_gchk_3
	s_mov_b32 s101, 2
	s_cmp_lg_u32 s94, 0x100
	s_cbranch_scc1 .Lmy_gchk_3
	v_readlane_b32 s8, v250, 0
	v_readlane_b32 s9, v250, 1
	s_mov_b32 s2, -1
	v_mbcnt_lo_u32_b32 v0, s2, 0
	v_mbcnt_hi_u32_b32 v0, s2, v0
	v_lshlrev_b32_e32 v0, 2, v0
	s_add_u32 s8, s8, 0x60000
	s_addc_u32 s9, s9, 0
	global_load_dword v1, v0, s[8:9] sc0 sc1
	global_load_dword v2, v0, s[8:9] offset:256 sc0 sc1
	global_load_dword v3, v0, s[8:9] offset:512 sc0 sc1
	global_load_dword v4, v0, s[8:9] offset:768 sc0 sc1
	v_and_b32_e32 v5, 28, v0
	global_load_dword v5, v5, s[8:9] sc0 sc1
	s_waitcnt vmcnt(0)
	v_cmp_eq_u32_e64 s[12:13], v1, v5
	s_nop 1
	v_cmp_ne_u32_e32 vcc, 0, v1
	v_cmp_eq_u32_e64 s[2:3], v1, v2
	s_and_b64 s[2:3], s[2:3], s[12:13]
	v_cmp_eq_u32_e64 s[12:13], v1, v3
	s_and_b64 s[2:3], s[2:3], vcc
	v_cmp_eq_u32_e64 s[8:9], v1, v4
	s_and_b64 s[2:3], s[2:3], s[12:13]
	s_and_b64 s[2:3], s[2:3], s[8:9]
	s_cmp_eq_u64 s[2:3], -1
	s_cbranch_scc0 .Lmy_gchk_3
	s_mov_b32 s101, 1

.LBB0_2088:
	s_mov_b64 s[42:43], 0
	s_and_b64 vcc, exec, s[28:29]
	s_cbranch_vccz .LBB0_2090
	s_ashr_i32 s26, s35, 3
	s_and_b32 s34, s35, 7
	s_cmp_lg_u32 s94, 0x100
	s_cbranch_scc1 .Lmy_ppmap
	v_readlane_b32 s98, v250, 7
	s_add_i32 s99, s98, 0xffffff40
	s_mul_i32 s99, s99, 5
	s_addk_i32 s99, 0xc0
	s_cmp_lt_u32 s98, 0xc0
	s_cselect_b32 s99, s98, s99
	s_sub_i32 s34, s35, s99
	s_lshr_b32 s99, s98, 6
	s_add_i32 s34, s34, s99
	s_and_b32 s26, s98, 7
	s_lshl_b32 s26, s26, 3
	s_bfe_u32 s99, s98, 0x30003
	s_or_b32 s26, s26, s99
.Lmy_ppmap:
	s_mov_b64 s[42:43], -1

.LBB0_2100:
	v_readlane_b32 s0, v253, 37
	v_readlane_b32 s16, v250, 0
	s_or_b32 s0, s0, 12
	v_readlane_b32 s19, v250, 3
	s_cmp_ge_i32 s0, s19
	v_readlane_b32 s17, v250, 1
	v_readlane_b32 s18, v250, 2
	s_cbranch_scc1 .LBB0_2156
	s_waitcnt vmcnt(0)
	v_readlane_b32 s2, v253, 40
	v_readlane_b32 s3, v253, 41
	s_and_b64 vcc, exec, s[2:3]
	s_waitcnt vmcnt(0) lgkmcnt(0)
	s_barrier
	s_cbranch_vccnz .LBB0_2155
	s_mov_b32 s2, -1
	s_nop 0
	v_mbcnt_lo_u32_b32 v0, s2, 0
	v_mbcnt_hi_u32_b32 v0, s2, v0
	s_nop 0
	v_cmp_eq_u32_e32 vcc, 0, v0
	s_and_saveexec_b64 s[16:17], vcc
	s_cbranch_execz .LBB0_2154
	s_cmp_lg_u32 s101, 1
	s_cbranch_scc1 .Lmy_gfull_6
	v_readlane_b32 s2, v253, 37
	v_readlane_b32 s3, v250, 7
	v_readlane_b32 s8, v250, 0
	v_readlane_b32 s9, v250, 1
	s_lshl_b32 s2, s2, 11
	s_add_i32 s2, s2, 0x6000
	s_add_u32 s8, s8, 0x70000
	s_addc_u32 s9, s9, 0
	s_and_b32 s12, s3, 7
	s_lshl_b32 s12, s12, 3
	s_bfe_u32 s13, s3, 0x30003
	s_or_b32 s12, s12, s13
	s_and_b32 s13, s12, 7
	s_cmp_lg_u32 s13, 7
	s_cbranch_scc1 .Lmy_g6_nowb
	s_and_b32 s13, s12, 31
	s_cmp_eq_u32 s13, 31
	s_cbranch_scc1 .Lmy_g6_nowb
	s_waitcnt vmcnt(0) lgkmcnt(0)
	buffer_wbl2 sc1
	s_waitcnt vmcnt(0)
.Lmy_g6_nowb:
	s_and_b32 s3, s3, 63
	s_lshl_b32 s3, s3, 6
	s_add_i32 s3, s2, s3
	v_mov_b32_e32 v0, s3
	v_mov_b32_e32 v1, 1
	s_waitcnt vmcnt(0) lgkmcnt(0)
	global_atomic_add v0, v1, s[8:9]
	s_and_b32 s13, s12, 31
	s_cmp_eq_u32 s13, 0
	s_cbranch_scc1 .Lmy_g6_self
	s_add_i32 s12, s12, -1
	s_and_b32 s13, s12, 7
	s_lshl_b32 s13, s13, 3
	s_lshr_b32 s12, s12, 3
	s_or_b32 s12, s12, s13
	s_lshl_b32 s12, s12, 6
	s_add_i32 s3, s2, s12
.Lmy_g6_self:
	v_mov_b32_e32 v3, s3
	s_mov_b32 s2, 0
.Lmy_gspin_6:
	global_load_dword v2, v0, s[8:9] sc1
	global_load_dword v4, v3, s[8:9] sc1
	s_waitcnt vmcnt(0)
	v_min_u32_e32 v2, v2, v4
	s_nop 1
	v_readfirstlane_b32 s3, v2
	s_cmp_ge_u32 s3, 4
	s_cbranch_scc1 .Lmy_gdone_6
	s_sleep 1
	s_add_i32 s2, s2, 1
	s_cmp_lt_u32 s2, 0x4000
	s_cbranch_scc1 .Lmy_gspin_6

.LBB0_2164:
	s_or_b64 exec, exec, s[8:9]
	v_readlane_b32 s0, v253, 37
	v_readlane_b32 s16, v250, 0
	s_or_b32 s0, s0, 13
	v_readlane_b32 s19, v250, 3
	s_cmp_ge_i32 s0, s19
	v_readlane_b32 s17, v250, 1
	v_readlane_b32 s18, v250, 2
	s_cbranch_scc1 .LBB0_2220
	s_waitcnt vmcnt(0)
	v_readlane_b32 s2, v253, 40
	v_readlane_b32 s3, v253, 41
	s_and_b64 vcc, exec, s[2:3]
	s_waitcnt vmcnt(0) lgkmcnt(0)
	s_barrier
	s_cbranch_vccnz .LBB0_2219
	s_cmp_lg_u32 s101, 0
	s_cbranch_scc1 .Lmy_gchk_5
	s_mov_b32 s101, 2
	s_cmp_lg_u32 s94, 0x100
	s_cbranch_scc1 .Lmy_gchk_5
	v_readlane_b32 s8, v250, 0
	v_readlane_b32 s9, v250, 1
	s_mov_b32 s2, -1
	v_mbcnt_lo_u32_b32 v0, s2, 0
	v_mbcnt_hi_u32_b32 v0, s2, v0
	v_lshlrev_b32_e32 v0, 2, v0
	s_add_u32 s8, s8, 0x60000
	s_addc_u32 s9, s9, 0
	global_load_dword v1, v0, s[8:9] sc0 sc1
	global_load_dword v2, v0, s[8:9] offset:256 sc0 sc1
	global_load_dword v3, v0, s[8:9] offset:512 sc0 sc1
	global_load_dword v4, v0, s[8:9] offset:768 sc0 sc1
	v_and_b32_e32 v5, 28, v0
	global_load_dword v5, v5, s[8:9] sc0 sc1
	s_waitcnt vmcnt(0)
	v_cmp_eq_u32_e64 s[12:13], v1, v5
	s_nop 1
	v_cmp_ne_u32_e32 vcc, 0, v1
	v_cmp_eq_u32_e64 s[2:3], v1, v2
	s_and_b64 s[2:3], s[2:3], s[12:13]
	v_cmp_eq_u32_e64 s[12:13], v1, v3
	s_and_b64 s[2:3], s[2:3], vcc
	v_cmp_eq_u32_e64 s[8:9], v1, v4
	s_and_b64 s[2:3], s[2:3], s[12:13]
	s_and_b64 s[2:3], s[2:3], s[8:9]
	s_cmp_eq_u64 s[2:3], -1
	s_cbranch_scc0 .Lmy_gchk_5
	s_mov_b32 s101, 1

.LBB0_2249:
	v_readlane_b32 s0, v253, 37
	v_readlane_b32 s16, v250, 0
	s_or_b32 s0, s0, 14
	v_readlane_b32 s19, v250, 3
	s_cmp_ge_i32 s0, s19
	v_readlane_b32 s17, v250, 1
	v_readlane_b32 s18, v250, 2
	s_cbranch_scc1 .LBB0_2305
	s_waitcnt vmcnt(0)
	v_readlane_b32 s2, v253, 40
	v_readlane_b32 s3, v253, 41
	s_and_b64 vcc, exec, s[2:3]
	s_waitcnt vmcnt(0) lgkmcnt(0)
	s_barrier
	s_cbranch_vccnz .LBB0_2304
	s_cmp_lg_u32 s101, 0
	s_cbranch_scc1 .Lmy_gchk_1
	s_mov_b32 s101, 2
	s_cmp_lg_u32 s94, 0x100
	s_cbranch_scc1 .Lmy_gchk_1
	v_readlane_b32 s8, v250, 0
	v_readlane_b32 s9, v250, 1
	s_mov_b32 s2, -1
	v_mbcnt_lo_u32_b32 v0, s2, 0
	v_mbcnt_hi_u32_b32 v0, s2, v0
	v_lshlrev_b32_e32 v0, 2, v0
	s_add_u32 s8, s8, 0x60000
	s_addc_u32 s9, s9, 0
	global_load_dword v1, v0, s[8:9] sc0 sc1
	global_load_dword v2, v0, s[8:9] offset:256 sc0 sc1
	global_load_dword v3, v0, s[8:9] offset:512 sc0 sc1
	global_load_dword v4, v0, s[8:9] offset:768 sc0 sc1
	v_and_b32_e32 v5, 28, v0
	global_load_dword v5, v5, s[8:9] sc0 sc1
	s_waitcnt vmcnt(0)
	v_cmp_eq_u32_e64 s[12:13], v1, v5
	s_nop 1
	v_cmp_ne_u32_e32 vcc, 0, v1
	v_cmp_eq_u32_e64 s[2:3], v1, v2
	s_and_b64 s[2:3], s[2:3], s[12:13]
	v_cmp_eq_u32_e64 s[12:13], v1, v3
	s_and_b64 s[2:3], s[2:3], vcc
	v_cmp_eq_u32_e64 s[8:9], v1, v4
	s_and_b64 s[2:3], s[2:3], s[12:13]
	s_and_b64 s[2:3], s[2:3], s[8:9]
	s_cmp_eq_u64 s[2:3], -1
	s_cbranch_scc0 .Lmy_gchk_1
	s_mov_b32 s101, 1

.LBB0_2327:
	v_readlane_b32 s0, v253, 37
	v_readlane_b32 s16, v250, 0
	s_or_b32 s0, s0, 15
	v_readlane_b32 s19, v250, 3
	s_cmp_ge_i32 s0, s19
	v_readlane_b32 s17, v250, 1
	v_readlane_b32 s18, v250, 2
	s_cbranch_scc1 .LBB0_2383
	s_waitcnt vmcnt(0)
	v_readlane_b32 s2, v253, 40
	v_readlane_b32 s3, v253, 41
	s_and_b64 vcc, exec, s[2:3]
	s_waitcnt vmcnt(0) lgkmcnt(0)
	s_barrier
	s_cbranch_vccnz .LBB0_2382
	s_cmp_lg_u32 s101, 0
	s_cbranch_scc1 .Lmy_gchk_2
	s_mov_b32 s101, 2
	s_cmp_lg_u32 s94, 0x100
	s_cbranch_scc1 .Lmy_gchk_2
	v_readlane_b32 s8, v250, 0
	v_readlane_b32 s9, v250, 1
	s_mov_b32 s2, -1
	v_mbcnt_lo_u32_b32 v0, s2, 0
	v_mbcnt_hi_u32_b32 v0, s2, v0
	v_lshlrev_b32_e32 v0, 2, v0
	s_add_u32 s8, s8, 0x60000
	s_addc_u32 s9, s9, 0
	global_load_dword v1, v0, s[8:9] sc0 sc1
	global_load_dword v2, v0, s[8:9] offset:256 sc0 sc1
	global_load_dword v3, v0, s[8:9] offset:512 sc0 sc1
	global_load_dword v4, v0, s[8:9] offset:768 sc0 sc1
	v_and_b32_e32 v5, 28, v0
	global_load_dword v5, v5, s[8:9] sc0 sc1
	s_waitcnt vmcnt(0)
	v_cmp_eq_u32_e64 s[12:13], v1, v5
	s_nop 1
	v_cmp_ne_u32_e32 vcc, 0, v1
	v_cmp_eq_u32_e64 s[2:3], v1, v2
	s_and_b64 s[2:3], s[2:3], s[12:13]
	v_cmp_eq_u32_e64 s[12:13], v1, v3
	s_and_b64 s[2:3], s[2:3], vcc
	v_cmp_eq_u32_e64 s[8:9], v1, v4
	s_and_b64 s[2:3], s[2:3], s[12:13]
	s_and_b64 s[2:3], s[2:3], s[8:9]
	s_cmp_eq_u64 s[2:3], -1
	s_cbranch_scc0 .Lmy_gchk_2
	s_mov_b32 s101, 1
